# cross-attention: last three Q row-piece loads issued with the first five at item start (fresh temps + v_mov), on top of SB K/V hoist, route preamble and RG setup batching
# speedup vs baseline: 1.0033x; 1.0033x over previous
; __device__ __forceinline__ u32x4 pack8(const float* f) { u32x4 o; o.x = pk2(f[0], f[1]); o.y = pk2(f[2], f[3]); o.z = pk2(f[4], f[5]); o.w = pk2(f[6], f[7]); return o; }
; __device__ __forceinline__ void phase_xattn(CArgs& A, int l, unsigned char* lds, int tid) {
;     ...
;     for (int it = blockIdx.x; it < BATCH * 4 * 16; it += gridDim.x) {
;         asm volatile("" : "+v"(tid));
;         const int wave = tid >> 6, lane = tid & 63, r = lane & 15, g = lane >> 4;
;         const int b = it >> 6, h = (it >> 4) & 3, qch = it & 15;
;         const size_t row = (size_t)b * SEQ + qch * 128 + wave * 16 + r;
;         bf16x8 qf[8];
; #pragma unroll
;         for (int ks = 0; ks < 8; ++ks) { float f[8]; unpack8(*(const u32x4*)(Q + row * DM + h * 256 + 32 * ks + 8 * g), f);
; #pragma unroll
;             for (int i = 0; i < 8; ++i) f[i] *= 0.0625f;
;             qf[ks] = __builtin_bit_cast(bf16x8, pack8(f)); }
;         f32x4 o[16];
; #pragma unroll
;         for (int i = 0; i < 16; ++i) o[i] = (f32x4){0.f, 0.f, 0.f, 0.f};
;         float m = -INFINITY, lsum = 0.f;
;         const int skey = tid >> 3, sdc = (tid & 7) * 32;
;         const bf16* kvbase = KV + ((size_t)b * NMEM + skey) * 4096 + l * 2048 + h * 256 + sdc;
;         u32x4 kr[4], vr[4];
; #pragma unroll
;         for (int i = 0; i < 4; ++i) { kr[i] = *(const u32x4*)(kvbase + i * 8); vr[i] = *(const u32x4*)(kvbase + 1024 + i * 8); }
.LBB0_144:
	s_ashr_i32 s4, s11, 6
	s_ashr_i32 s5, s4, 31
	s_lshl_b32 s8, s11, 7
	s_lshl_b64 s[0:1], s[4:5], 11
	s_and_b32 s8, s8, 0x780
	v_ashrrev_i32_e32 v2, 2, v1
	v_and_b32_e32 v36, 15, v1
	s_or_b32 s0, s0, s8
	v_and_b32_e32 v2, -16, v2
	v_ashrrev_i32_e32 v3, 31, v2
	v_or_b32_e32 v4, s0, v36
	v_mov_b32_e32 v5, s1
	v_lshl_add_u64 v[2:3], v[4:5], 0, v[2:3]
	s_lshl_b32 s0, s11, 4
	v_lshlrev_b64 v[144:145], 11, v[2:3]
	s_and_b32 s36, s0, 0x300
	v_bfe_u32 v37, v1, 4, 2
	v_lshl_add_u64 v[2:3], s[38:39], 0, v[144:145]
	s_lshl_b32 s14, s36, 1
	v_lshl_add_u64 v[2:3], v[2:3], 0, s[14:15]
	v_lshlrev_b32_e32 v34, 4, v37
	v_mov_b32_e32 v35, v0
	v_lshl_add_u64 v[22:23], v[2:3], 0, v[34:35]
	v_ashrrev_i32_e32 v204, 3, v1
	s_lshl_b64 s[98:99], s[4:5], 21
	v_ashrrev_i32_e32 v205, 31, v204
	s_add_u32 s98, s9, s98
	s_addc_u32 s99, s10, s99
	v_lshlrev_b64 v[206:207], 13, v[204:205]
	v_lshl_add_u64 v[208:209], s[98:99], 0, v[206:207]
	v_lshl_add_u64 v[208:209], s[40:41], 1, v[208:209]
	v_lshlrev_b32_e32 v206, 6, v1
	v_lshl_add_u64 v[208:209], v[208:209], 0, s[14:15]
	v_and_b32_e32 v206, 0x1c0, v206
	v_mov_b32_e32 v207, v0
	v_lshl_add_u64 v[208:209], v[208:209], 0, v[206:207]
	global_load_dwordx4 v[102:105], v[208:209], off offset:32
	global_load_dwordx4 v[106:109], v[208:209], off offset:16
	global_load_dwordx4 v[110:113], v[208:209], off
	global_load_dwordx4 v[114:117], v[208:209], off offset:2096
	global_load_dwordx4 v[118:121], v[208:209], off offset:2080
	global_load_dwordx4 v[122:125], v[208:209], off offset:2064
	global_load_dwordx4 v[126:129], v[208:209], off offset:2048
	global_load_dwordx4 v[2:5], v[22:23], off
	global_load_dwordx4 v[6:9], v[22:23], off offset:64
	global_load_dwordx4 v[10:13], v[22:23], off offset:128
	global_load_dwordx4 v[14:17], v[22:23], off offset:192
	global_load_dwordx4 v[18:21], v[22:23], off offset:256
	global_load_dwordx4 v[212:215], v[22:23], off offset:320
	global_load_dwordx4 v[216:219], v[22:23], off offset:384
	global_load_dwordx4 v[220:223], v[22:23], off offset:448
	s_mov_b32 s0, 0x3d800000
	v_mov_b32_e32 v147, v0
	v_cmp_lt_i32_e32 vcc, v178, v173
	v_lshlrev_b32_e32 v143, 2, v37
	v_and_b32_e32 v37, 7, v1
	v_lshlrev_b32_e32 v37, 6, v37
	v_mul_u32_u24_e32 v36, 0x220, v36
	v_mov_b32_e32 v130, 0
	v_mov_b32_e32 v156, 0xff800000
	s_mov_b64 s[44:45], 0
	v_mov_b32_e32 v51, v130
	s_waitcnt lgkmcnt(0)
	v_mov_b32_e32 v52, v130
	s_waitcnt lgkmcnt(2)
	v_mov_b32_e32 v53, v130
	v_mov_b32_e32 v54, 0
	v_mov_b32_e32 v55, v130
	s_waitcnt lgkmcnt(1)
	v_mov_b32_e32 v56, v130
	s_waitcnt lgkmcnt(0)
	v_mov_b32_e32 v57, v130
	v_mov_b32_e32 v58, 0
	v_mov_b32_e32 v59, v130
	v_mov_b32_e32 v60, v130
	v_mov_b32_e32 v61, v130
	v_mov_b32_e32 v74, 0
	v_mov_b32_e32 v75, v130
	v_mov_b32_e32 v76, v130
	v_mov_b32_e32 v77, v130
	s_waitcnt vmcnt(0)
	v_mov_b32_e32 v94, 0
	v_mov_b32_e32 v95, v130
	v_mov_b32_e32 v96, v130
	v_mov_b32_e32 v97, v130
	v_mov_b32_e32 v82, 0
	v_mov_b32_e32 v83, v130
	v_mov_b32_e32 v84, v130
	v_mov_b32_e32 v85, v130
	v_mov_b32_e32 v90, 0
	v_mov_b32_e32 v91, v130
	v_mov_b32_e32 v92, v130
	v_mov_b32_e32 v93, v130
	v_mov_b32_e32 v78, 0
	v_mov_b32_e32 v79, v130
	v_mov_b32_e32 v80, v130
	v_mov_b32_e32 v81, v130
	v_mov_b32_e32 v70, 0
	v_mov_b32_e32 v71, v130
	v_mov_b32_e32 v72, v130
	v_mov_b32_e32 v73, v130
	v_mov_b32_e32 v62, 0
	v_mov_b32_e32 v63, v130
	v_mov_b32_e32 v64, v130
	v_mov_b32_e32 v65, v130
	v_mov_b32_e32 v66, 0
	v_mov_b32_e32 v67, v130
	v_mov_b32_e32 v68, v130
	v_mov_b32_e32 v69, v130
	v_mov_b32_e32 v86, 0
	v_mov_b32_e32 v87, v130
	v_mov_b32_e32 v88, v130
	v_mov_b32_e32 v89, v130
	s_waitcnt vmcnt(4)
	v_lshlrev_b32_e32 v25, 16, v3
	v_lshlrev_b32_e32 v24, 16, v2
	v_and_b32_e32 v3, 0xffff0000, v3
	v_and_b32_e32 v2, 0xffff0000, v2
	v_lshlrev_b32_e32 v27, 16, v5
	v_lshlrev_b32_e32 v26, 16, v4
	v_and_b32_e32 v5, 0xffff0000, v5
	v_and_b32_e32 v4, 0xffff0000, v4
	s_waitcnt vmcnt(3)
	v_lshlrev_b32_e32 v29, 16, v7
	v_lshlrev_b32_e32 v28, 16, v6
	v_and_b32_e32 v7, 0xffff0000, v7
	v_and_b32_e32 v6, 0xffff0000, v6
	v_lshlrev_b32_e32 v31, 16, v9
	v_lshlrev_b32_e32 v30, 16, v8
	v_and_b32_e32 v9, 0xffff0000, v9
	v_and_b32_e32 v8, 0xffff0000, v8
	v_pk_mul_f32 v[24:25], v[24:25], s[0:1] op_sel_hi:[1,0]
	v_pk_mul_f32 v[2:3], v[2:3], s[0:1] op_sel_hi:[1,0]
	v_pk_mul_f32 v[26:27], v[26:27], s[0:1] op_sel_hi:[1,0]
	v_pk_mul_f32 v[4:5], v[4:5], s[0:1] op_sel_hi:[1,0]
	v_pk_mul_f32 v[28:29], v[28:29], s[0:1] op_sel_hi:[1,0]
	v_pk_mul_f32 v[6:7], v[6:7], s[0:1] op_sel_hi:[1,0]
	v_pk_mul_f32 v[30:31], v[30:31], s[0:1] op_sel_hi:[1,0]
	v_pk_mul_f32 v[8:9], v[8:9], s[0:1] op_sel_hi:[1,0]
	v_bfe_u32 v39, v24, 16, 1
	v_bfe_u32 v32, v5, 16, 1
	v_bfe_u32 v35, v3, 16, 1
	v_bfe_u32 v38, v2, 16, 1
	v_bfe_u32 v40, v25, 16, 1
	v_bfe_u32 v41, v26, 16, 1
	v_bfe_u32 v42, v27, 16, 1
	v_bfe_u32 v44, v8, 16, 1
	v_bfe_u32 v46, v6, 16, 1
	v_bfe_u32 v47, v28, 16, 1
	v_bfe_u32 v49, v30, 16, 1
	v_bfe_u32 v50, v31, 16, 1
	v_add3_u32 v24, v24, v39, s84
	v_bfe_u32 v33, v4, 16, 1
	v_bfe_u32 v43, v9, 16, 1
	v_bfe_u32 v45, v7, 16, 1
	v_bfe_u32 v48, v29, 16, 1
	v_add3_u32 v2, v2, v38, s84
	v_add3_u32 v3, v3, v35, s84
	v_add3_u32 v5, v5, v32, s84
	v_add3_u32 v27, v27, v42, s84
	v_add3_u32 v26, v26, v41, s84
	v_add3_u32 v25, v25, v40, s84
	v_add3_u32 v32, v6, v46, s84
	v_add3_u32 v35, v8, v44, s84
	v_add3_u32 v31, v31, v50, s84
	v_add3_u32 v6, v30, v49, s84
	v_add3_u32 v8, v28, v47, s84
	v_lshrrev_b32_e32 v24, 16, v24
	v_add3_u32 v4, v4, v33, s84
	v_add3_u32 v33, v7, v45, s84
	v_add3_u32 v38, v9, v43, s84
	v_add3_u32 v7, v29, v48, s84
	v_lshrrev_b32_e32 v25, 16, v25
	v_lshrrev_b32_e32 v26, 16, v26
	v_lshrrev_b32_e32 v9, 16, v27
	v_lshrrev_b32_e32 v27, 16, v8
	v_lshrrev_b32_e32 v29, 16, v6
	v_and_or_b32 v6, v2, s3, v24
	v_lshrrev_b32_e32 v2, 16, v31
	v_lshrrev_b32_e32 v28, 16, v7
	v_and_or_b32 v9, v5, s3, v9
	v_and_or_b32 v8, v4, s3, v26
	v_and_or_b32 v7, v3, s3, v25
	v_and_or_b32 v5, v38, s3, v2
	v_and_or_b32 v2, v32, s3, v27
	s_waitcnt vmcnt(2)
; __device__ __forceinline__ u32x4 pack8(const float* f) { u32x4 o; o.x = pk2(f[0], f[1]); o.y = pk2(f[2], f[3]); o.z = pk2(f[4], f[5]); o.w = pk2(f[6], f[7]); return o; }
; __device__ __forceinline__ void phase_xattn(CArgs& A, int l, unsigned char* lds, int tid) {
;     ...
;         for (int ks = 0; ks < 8; ++ks) { float f[8]; unpack8(*(const u32x4*)(Q + row * DM + h * 256 + 32 * ks + 8 * g), f);
; #pragma unroll
;             for (int i = 0; i < 8; ++i) f[i] *= 0.0625f;
;             qf[ks] = __builtin_bit_cast(bf16x8, pack8(f)); }
	v_lshlrev_b32_e32 v25, 16, v11
	v_lshlrev_b32_e32 v24, 16, v10
	v_and_b32_e32 v11, 0xffff0000, v11
	v_and_b32_e32 v10, 0xffff0000, v10
	v_lshlrev_b32_e32 v27, 16, v13
	v_lshlrev_b32_e32 v26, 16, v12
	v_and_b32_e32 v13, 0xffff0000, v13
	v_and_b32_e32 v12, 0xffff0000, v12
	v_pk_mul_f32 v[10:11], v[10:11], s[0:1] op_sel_hi:[1,0]
	v_pk_mul_f32 v[12:13], v[12:13], s[0:1] op_sel_hi:[1,0]
	v_and_or_b32 v4, v35, s3, v29
	v_and_or_b32 v3, v33, s3, v28
	v_pk_mul_f32 v[24:25], v[24:25], s[0:1] op_sel_hi:[1,0]
	v_pk_mul_f32 v[26:27], v[26:27], s[0:1] op_sel_hi:[1,0]
	v_bfe_u32 v28, v13, 16, 1
	v_bfe_u32 v29, v12, 16, 1
	v_bfe_u32 v30, v11, 16, 1
	v_bfe_u32 v31, v10, 16, 1
	v_add3_u32 v10, v10, v31, s84
	v_add3_u32 v11, v11, v30, s84
	v_add3_u32 v12, v12, v29, s84
	v_add3_u32 v13, v13, v28, s84
	v_bfe_u32 v28, v24, 16, 1
	v_bfe_u32 v29, v25, 16, 1
	v_bfe_u32 v30, v26, 16, 1
	v_bfe_u32 v31, v27, 16, 1
	v_add3_u32 v31, v27, v31, s84
	v_add3_u32 v26, v26, v30, s84
	v_add3_u32 v25, v25, v29, s84
	v_add3_u32 v24, v24, v28, s84
	v_lshrrev_b32_e32 v28, 16, v24
	v_lshrrev_b32_e32 v29, 16, v25
	v_lshrrev_b32_e32 v30, 16, v26
	v_mov_b32_e32 v24, v212
	v_mov_b32_e32 v25, v213
	v_mov_b32_e32 v26, v214
	v_mov_b32_e32 v27, v215
	v_lshrrev_b32_e32 v31, 16, v31
	v_and_or_b32 v13, v13, s3, v31
	v_and_or_b32 v12, v12, s3, v30
	s_waitcnt vmcnt(2)
	v_lshlrev_b32_e32 v31, 16, v17
	v_lshlrev_b32_e32 v30, 16, v16
	v_and_b32_e32 v17, 0xffff0000, v17
	v_and_b32_e32 v16, 0xffff0000, v16
	v_and_or_b32 v11, v11, s3, v29
	v_and_or_b32 v10, v10, s3, v28
	v_lshlrev_b32_e32 v29, 16, v15
	v_lshlrev_b32_e32 v28, 16, v14
	v_and_b32_e32 v15, 0xffff0000, v15
	v_and_b32_e32 v14, 0xffff0000, v14
	v_pk_mul_f32 v[16:17], v[16:17], s[0:1] op_sel_hi:[1,0]
	v_pk_mul_f32 v[28:29], v[28:29], s[0:1] op_sel_hi:[1,0]
	v_pk_mul_f32 v[14:15], v[14:15], s[0:1] op_sel_hi:[1,0]
	v_bfe_u32 v32, v17, 16, 1
	v_bfe_u32 v33, v16, 16, 1
	v_pk_mul_f32 v[30:31], v[30:31], s[0:1] op_sel_hi:[1,0]
	v_bfe_u32 v35, v15, 16, 1
	v_bfe_u32 v38, v14, 16, 1
	v_add3_u32 v16, v16, v33, s84
	v_add3_u32 v17, v17, v32, s84
	v_bfe_u32 v32, v28, 16, 1
	v_bfe_u32 v33, v29, 16, 1
	v_add3_u32 v14, v14, v38, s84
	v_add3_u32 v15, v15, v35, s84
	v_bfe_u32 v35, v30, 16, 1
	v_bfe_u32 v38, v31, 16, 1
	v_add3_u32 v29, v29, v33, s84
	v_add3_u32 v28, v28, v32, s84
	v_add3_u32 v38, v31, v38, s84
	v_add3_u32 v35, v30, v35, s84
	v_lshrrev_b32_e32 v32, 16, v28
	v_lshrrev_b32_e32 v33, 16, v29
	v_mov_b32_e32 v28, v216
	v_mov_b32_e32 v29, v217
	v_mov_b32_e32 v30, v218
	v_mov_b32_e32 v31, v219
	v_lshrrev_b32_e32 v38, 16, v38
	v_and_or_b32 v17, v17, s3, v38
	v_and_or_b32 v15, v15, s3, v33
	v_and_or_b32 v14, v14, s3, v32
	s_waitcnt vmcnt(2)
	v_lshlrev_b32_e32 v33, 16, v19
	v_lshlrev_b32_e32 v32, 16, v18
	v_and_b32_e32 v19, 0xffff0000, v19
	v_and_b32_e32 v18, 0xffff0000, v18
	v_lshlrev_b32_e32 v39, 16, v21
	v_lshlrev_b32_e32 v38, 16, v20
	v_and_b32_e32 v21, 0xffff0000, v21
	v_and_b32_e32 v20, 0xffff0000, v20
	v_pk_mul_f32 v[18:19], v[18:19], s[0:1] op_sel_hi:[1,0]
	v_pk_mul_f32 v[20:21], v[20:21], s[0:1] op_sel_hi:[1,0]
	v_pk_mul_f32 v[32:33], v[32:33], s[0:1] op_sel_hi:[1,0]
	v_pk_mul_f32 v[38:39], v[38:39], s[0:1] op_sel_hi:[1,0]
	v_bfe_u32 v40, v20, 16, 1
	v_bfe_u32 v41, v19, 16, 1
	v_bfe_u32 v42, v18, 16, 1
	v_add3_u32 v18, v18, v42, s84
	v_add3_u32 v19, v19, v41, s84
	v_add3_u32 v20, v20, v40, s84
	v_bfe_u32 v40, v33, 16, 1
	v_bfe_u32 v41, v38, 16, 1
	v_bfe_u32 v42, v39, 16, 1
	v_add3_u32 v42, v39, v42, s84
	v_add3_u32 v43, v38, v41, s84
	v_add3_u32 v33, v33, v40, s84
	v_mov_b32_e32 v38, v220
	v_mov_b32_e32 v39, v221
	v_mov_b32_e32 v40, v222
	v_mov_b32_e32 v41, v223
	v_lshrrev_b32_e32 v35, 16, v35
	v_and_or_b32 v16, v16, s3, v35
	v_bfe_u32 v35, v21, 16, 1
	v_add3_u32 v21, v21, v35, s84
	v_bfe_u32 v35, v32, 16, 1
	v_add3_u32 v32, v32, v35, s84
	v_lshrrev_b32_e32 v32, 16, v32
	v_lshrrev_b32_e32 v22, 16, v33
	v_lshrrev_b32_e32 v23, 16, v43
	v_lshrrev_b32_e32 v33, 16, v42
	v_and_or_b32 v21, v21, s3, v33
	v_and_or_b32 v20, v20, s3, v23
	v_and_or_b32 v19, v19, s3, v22
	v_and_or_b32 v18, v18, s3, v32
	s_waitcnt vmcnt(2)
	v_lshlrev_b32_e32 v23, 16, v25
	v_lshlrev_b32_e32 v22, 16, v24
	v_and_b32_e32 v25, 0xffff0000, v25
	v_and_b32_e32 v24, 0xffff0000, v24
	v_lshlrev_b32_e32 v33, 16, v27
	v_lshlrev_b32_e32 v32, 16, v26
	v_and_b32_e32 v27, 0xffff0000, v27
	v_and_b32_e32 v26, 0xffff0000, v26
	v_pk_mul_f32 v[24:25], v[24:25], s[0:1] op_sel_hi:[1,0]
	v_pk_mul_f32 v[26:27], v[26:27], s[0:1] op_sel_hi:[1,0]
	v_pk_mul_f32 v[32:33], v[32:33], s[0:1] op_sel_hi:[1,0]
	v_bfe_u32 v35, v27, 16, 1
	v_bfe_u32 v42, v26, 16, 1
	v_bfe_u32 v43, v25, 16, 1
	v_bfe_u32 v44, v24, 16, 1
	v_pk_mul_f32 v[22:23], v[22:23], s[0:1] op_sel_hi:[1,0]
	v_add3_u32 v44, v24, v44, s84
	v_add3_u32 v43, v25, v43, s84
	v_add3_u32 v24, v26, v42, s84
	v_add3_u32 v25, v27, v35, s84
	v_bfe_u32 v35, v32, 16, 1
	v_bfe_u32 v42, v33, 16, 1
	v_bfe_u32 v26, v22, 16, 1
	v_bfe_u32 v27, v23, 16, 1
	v_add3_u32 v33, v33, v42, s84
	v_add3_u32 v32, v32, v35, s84
	v_add3_u32 v23, v23, v27, s84
	v_add3_u32 v22, v22, v26, s84
	v_lshrrev_b32_e32 v26, 16, v32
	v_lshrrev_b32_e32 v27, 16, v33
	v_and_or_b32 v25, v25, s3, v27
	v_and_or_b32 v24, v24, s3, v26
	v_lshrrev_b32_e32 v22, 16, v22
	v_lshrrev_b32_e32 v23, 16, v23
	v_and_or_b32 v23, v43, s3, v23
	v_and_or_b32 v22, v44, s3, v22
	s_waitcnt vmcnt(1)
; __device__ __forceinline__ u32x4 pack8(const float* f) { u32x4 o; o.x = pk2(f[0], f[1]); o.y = pk2(f[2], f[3]); o.z = pk2(f[4], f[5]); o.w = pk2(f[6], f[7]); return o; }
; __device__ __forceinline__ void phase_xattn(CArgs& A, int l, unsigned char* lds, int tid) {
;     ...
;         for (int ks = 0; ks < 8; ++ks) { float f[8]; unpack8(*(const u32x4*)(Q + row * DM + h * 256 + 32 * ks + 8 * g), f);
; #pragma unroll
;             for (int i = 0; i < 8; ++i) f[i] *= 0.0625f;
;             qf[ks] = __builtin_bit_cast(bf16x8, pack8(f)); }
;         f32x4 o[16];
; #pragma unroll
;         for (int i = 0; i < 16; ++i) o[i] = (f32x4){0.f, 0.f, 0.f, 0.f};
;         float m = -INFINITY, lsum = 0.f;
;         const int skey = tid >> 3, sdc = (tid & 7) * 32;
;         const bf16* kvbase = KV + ((size_t)b * NMEM + skey) * 4096 + l * 2048 + h * 256 + sdc;
;         u32x4 kr[4], vr[4];
; #pragma unroll
;         for (int i = 0; i < 4; ++i) { kr[i] = *(const u32x4*)(kvbase + i * 8); vr[i] = *(const u32x4*)(kvbase + 1024 + i * 8); }
	v_lshlrev_b32_e32 v27, 16, v29
	v_lshlrev_b32_e32 v26, 16, v28
	v_and_b32_e32 v29, 0xffff0000, v29
	v_and_b32_e32 v28, 0xffff0000, v28
	v_lshlrev_b32_e32 v33, 16, v31
	v_lshlrev_b32_e32 v32, 16, v30
	v_and_b32_e32 v31, 0xffff0000, v31
	v_and_b32_e32 v30, 0xffff0000, v30
	v_pk_mul_f32 v[28:29], v[28:29], s[0:1] op_sel_hi:[1,0]
	v_pk_mul_f32 v[30:31], v[30:31], s[0:1] op_sel_hi:[1,0]
	v_pk_mul_f32 v[32:33], v[32:33], s[0:1] op_sel_hi:[1,0]
	v_bfe_u32 v35, v31, 16, 1
	v_bfe_u32 v42, v30, 16, 1
	v_bfe_u32 v43, v29, 16, 1
	v_bfe_u32 v44, v28, 16, 1
	v_pk_mul_f32 v[26:27], v[26:27], s[0:1] op_sel_hi:[1,0]
	v_add3_u32 v44, v28, v44, s84
	v_add3_u32 v43, v29, v43, s84
	v_add3_u32 v28, v30, v42, s84
	v_add3_u32 v29, v31, v35, s84
	v_bfe_u32 v35, v32, 16, 1
	v_bfe_u32 v42, v33, 16, 1
	v_bfe_u32 v30, v26, 16, 1
	v_bfe_u32 v31, v27, 16, 1
	v_add3_u32 v33, v33, v42, s84
	v_add3_u32 v32, v32, v35, s84
	v_add3_u32 v27, v27, v31, s84
	v_add3_u32 v26, v26, v30, s84
	v_lshrrev_b32_e32 v30, 16, v32
	v_lshrrev_b32_e32 v31, 16, v33
	v_and_or_b32 v29, v29, s3, v31
	v_and_or_b32 v28, v28, s3, v30
	s_waitcnt vmcnt(0)
	v_lshlrev_b32_e32 v31, 16, v39
	v_lshlrev_b32_e32 v30, 16, v38
	v_and_b32_e32 v33, 0xffff0000, v39
	v_and_b32_e32 v32, 0xffff0000, v38
	v_lshlrev_b32_e32 v39, 16, v41
	v_lshlrev_b32_e32 v38, 16, v40
	v_and_b32_e32 v41, 0xffff0000, v41
	v_and_b32_e32 v40, 0xffff0000, v40
	v_lshrrev_b32_e32 v26, 16, v26
	v_lshrrev_b32_e32 v27, 16, v27
	v_pk_mul_f32 v[32:33], v[32:33], s[0:1] op_sel_hi:[1,0]
	v_pk_mul_f32 v[40:41], v[40:41], s[0:1] op_sel_hi:[1,0]
	v_and_or_b32 v27, v43, s3, v27
	v_and_or_b32 v26, v44, s3, v26
	v_pk_mul_f32 v[38:39], v[38:39], s[0:1] op_sel_hi:[1,0]
	v_bfe_u32 v35, v41, 16, 1
	v_bfe_u32 v42, v40, 16, 1
	v_bfe_u32 v43, v33, 16, 1
	v_bfe_u32 v44, v32, 16, 1
	v_pk_mul_f32 v[30:31], v[30:31], s[0:1] op_sel_hi:[1,0]
	v_add3_u32 v44, v32, v44, s84
	v_add3_u32 v43, v33, v43, s84
	v_add3_u32 v32, v40, v42, s84
	v_add3_u32 v33, v41, v35, s84
	v_bfe_u32 v41, v38, 16, 1
	v_bfe_u32 v42, v39, 16, 1
	v_bfe_u32 v35, v30, 16, 1
	v_add3_u32 v39, v39, v42, s84
	v_add3_u32 v38, v38, v41, s84
	v_add3_u32 v30, v30, v35, s84
	v_lshrrev_b32_e32 v35, 16, v38
	v_lshrrev_b32_e32 v38, 16, v39
	v_bfe_u32 v40, v31, 16, 1
	v_and_or_b32 v33, v33, s3, v38
	v_ashrrev_i32_e32 v38, 3, v1
	s_lshl_b64 s[0:1], s[4:5], 21
	v_add3_u32 v31, v31, v40, s84
	v_ashrrev_i32_e32 v39, 31, v38
	s_add_u32 s4, s9, s0
	v_lshrrev_b32_e32 v31, 16, v31
	s_addc_u32 s5, s10, s1
	v_lshlrev_b64 v[40:41], 13, v[38:39]
	v_and_or_b32 v31, v43, s3, v31
	v_lshl_add_u64 v[42:43], s[4:5], 0, v[40:41]
	v_and_or_b32 v32, v32, s3, v35
	v_lshl_add_u64 v[42:43], s[40:41], 1, v[42:43]
	v_lshlrev_b32_e32 v35, 6, v1
	v_lshl_add_u64 v[42:43], v[42:43], 0, s[14:15]
	v_and_b32_e32 v146, 0x1c0, v35
	v_lshl_add_u64 v[42:43], v[42:43], 0, v[146:147]
	global_load_dwordx4 v[98:101], v[42:43], off offset:48
	v_add_u32_e32 v39, 0, v34
	v_cndmask_b32_e32 v34, v167, v178, vcc
	v_cmp_lt_i32_e32 vcc, v179, v173
	s_movk_i32 s4, 0x220
	v_lshlrev_b32_e32 v151, 2, v34
	v_cndmask_b32_e32 v34, v167, v179, vcc
	v_mul_lo_u32 v35, v38, s4
	v_lshlrev_b32_e32 v147, 2, v34
	v_bfe_u32 v34, v1, 2, 2
	v_add_u32_e32 v154, 0, v35
	v_or_b32_e32 v34, v143, v34
	v_lshlrev_b32_e32 v35, 3, v1
	v_and_b32_e32 v35, 24, v35
	v_mul_u32_u24_e32 v34, 0x220, v34
	v_add3_u32 v152, 0, v35, v34
	v_lshl_add_u64 v[34:35], s[0:1], 0, v[40:41]
	s_lshl_b32 s0, s11, 5
	s_and_b32 s0, s0, 0x600
	v_lshrrev_b32_e32 v30, 16, v30
	v_mov_b32_e32 v38, v154
	v_or3_b32 v34, v34, s0, v37
	v_and_or_b32 v30, v44, s3, v30
	v_lshl_add_u64 v[148:149], s[42:43], 0, v[34:35]
	v_add_u32_e32 v155, v38, v146
	v_add_u32_e32 v153, v39, v36
	v_mov_b32_e32 v34, 0
	v_mov_b32_e32 v35, v130
	v_mov_b32_e32 v36, v130
	v_mov_b32_e32 v37, v130
	v_mov_b32_e32 v38, 0
	v_mov_b32_e32 v39, v130
	v_mov_b32_e32 v40, v130
	v_mov_b32_e32 v41, v130
	v_mov_b32_e32 v42, 0
	v_mov_b32_e32 v43, v130
	v_mov_b32_e32 v44, v130
	v_mov_b32_e32 v45, v130
	v_mov_b32_e32 v46, 0
	v_mov_b32_e32 v47, v130
	v_mov_b32_e32 v48, v130
	v_mov_b32_e32 v49, v130
	v_mov_b32_e32 v50, 0
	s_waitcnt vmcnt(0)
